# v088 + hand-written adaLN GEMV loop (saddr loads, packed even/odd-k accumulators) + layer-1 GEMV done by retention workgroups in layer 0's mixer phase (3 units each)
# speedup vs baseline: 1.0053x; 1.0039x over previous
.LBB0_33:
	s_ashr_i32 s49, s48, 31
	v_lshl_add_u64 v[10:11], s[48:49], 2, v[6:7]
	s_movk_i32 s0, 0xf800
	v_mov_b32_e32 v132, 0
	v_mov_b32_e32 v133, 0
	v_mov_b32_e32 v134, 0
	v_mov_b32_e32 v135, 0
	v_mov_b32_e32 v136, 0
	v_mov_b32_e32 v137, 0
	v_mov_b32_e32 v138, 0
	v_mov_b32_e32 v139, 0
	v_mov_b32_e32 v140, 0
	v_mov_b32_e32 v141, 0
	v_readfirstlane_b32 s98, v10
	v_readfirstlane_b32 s99, v11
	s_nop 1
	v_subrev_u32_e32 v142, s98, v10
	s_sub_u32 s98, s98, 0x54000
	s_subb_u32 s99, s99, 0
.LBB0_34:
	global_load_dword v146, v142, s[98:99] nt
	s_add_u32 s98, s98, 0xc000
	s_addc_u32 s99, s99, 0
	global_load_dword v147, v142, s[98:99] nt
	s_add_u32 s98, s98, 0xc000
	s_addc_u32 s99, s99, 0
	global_load_dword v148, v142, s[98:99] nt
	s_add_u32 s98, s98, 0xc000
	s_addc_u32 s99, s99, 0
	global_load_dword v149, v142, s[98:99] nt
	s_add_u32 s98, s98, 0xc000
	s_addc_u32 s99, s99, 0
	global_load_dword v150, v142, s[98:99] nt
	s_add_u32 s98, s98, 0xc000
	s_addc_u32 s99, s99, 0
	global_load_dword v151, v142, s[98:99] nt
	s_add_u32 s98, s98, 0xc000
	s_addc_u32 s99, s99, 0
	global_load_dword v152, v142, s[98:99] nt
	s_add_u32 s98, s98, 0xc000
	s_addc_u32 s99, s99, 0
	global_load_dword v153, v142, s[98:99] nt
	s_add_u32 s98, s98, 0xc000
	s_addc_u32 s99, s99, 0
	global_load_dword v154, v142, s[98:99] nt
	s_add_u32 s98, s98, 0xc000
	s_addc_u32 s99, s99, 0
	global_load_dword v155, v142, s[98:99] nt
	s_add_u32 s98, s98, 0xc000
	s_addc_u32 s99, s99, 0
	global_load_dword v156, v142, s[98:99] nt
	s_add_u32 s98, s98, 0xc000
	s_addc_u32 s99, s99, 0
	global_load_dword v157, v142, s[98:99] nt
	s_add_u32 s98, s98, 0xc000
	s_addc_u32 s99, s99, 0
	global_load_dword v158, v142, s[98:99] nt
	s_add_u32 s98, s98, 0xc000
	s_addc_u32 s99, s99, 0
	global_load_dword v159, v142, s[98:99] nt
	s_add_u32 s98, s98, 0xc000
	s_addc_u32 s99, s99, 0
	global_load_dword v160, v142, s[98:99] nt
	s_add_u32 s98, s98, 0xc000
	s_addc_u32 s99, s99, 0
	global_load_dword v161, v142, s[98:99] nt
	s_add_u32 s98, s98, 0xc000
	s_addc_u32 s99, s99, 0
	global_load_dword v162, v142, s[98:99] nt
	s_add_u32 s98, s98, 0xc000
	s_addc_u32 s99, s99, 0
	global_load_dword v163, v142, s[98:99] nt
	s_add_u32 s98, s98, 0xc000
	s_addc_u32 s99, s99, 0
	global_load_dword v164, v142, s[98:99] nt
	s_add_u32 s98, s98, 0xc000
	s_addc_u32 s99, s99, 0
	global_load_dword v165, v142, s[98:99] nt
	s_add_u32 s98, s98, 0xc000
	s_addc_u32 s99, s99, 0
	global_load_dword v166, v142, s[98:99] nt
	s_add_u32 s98, s98, 0xc000
	s_addc_u32 s99, s99, 0
	global_load_dword v167, v142, s[98:99] nt
	s_add_u32 s98, s98, 0xc000
	s_addc_u32 s99, s99, 0
	global_load_dword v168, v142, s[98:99] nt
	s_add_u32 s98, s98, 0xc000
	s_addc_u32 s99, s99, 0
	global_load_dword v169, v142, s[98:99] nt
	s_add_u32 s98, s98, 0xc000
	s_addc_u32 s99, s99, 0
	global_load_dword v170, v142, s[98:99] nt
	s_add_u32 s98, s98, 0xc000
	s_addc_u32 s99, s99, 0
	global_load_dword v171, v142, s[98:99] nt
	s_add_u32 s98, s98, 0xc000
	s_addc_u32 s99, s99, 0
	global_load_dword v172, v142, s[98:99] nt
	s_add_u32 s98, s98, 0xc000
	s_addc_u32 s99, s99, 0
	global_load_dword v173, v142, s[98:99] nt
	s_add_u32 s98, s98, 0xc000
	s_addc_u32 s99, s99, 0
	global_load_dword v174, v142, s[98:99] nt
	s_add_u32 s98, s98, 0xc000
	s_addc_u32 s99, s99, 0
	global_load_dword v175, v142, s[98:99] nt
	s_add_u32 s98, s98, 0xc000
	s_addc_u32 s99, s99, 0
	global_load_dword v176, v142, s[98:99] nt
	s_add_u32 s98, s98, 0xc000
	s_addc_u32 s99, s99, 0
	global_load_dword v177, v142, s[98:99] nt
	s_add_u32 s98, s98, 0xc000
	s_addc_u32 s99, s99, 0
	s_add_i32 s46, s2, s0
	v_mov_b32_e32 v143, s46
	v_add_u32_e32 v144, 0x10800, v143
	ds_read_b128 v[22:25], v143 offset:2048
	ds_read_b128 v[26:29], v143 offset:2064
	ds_read_b128 v[30:33], v143 offset:18432
	ds_read_b128 v[34:37], v143 offset:18448
	ds_read_b128 v[38:41], v143 offset:34816
	ds_read_b128 v[42:45], v143 offset:34832
	ds_read_b128 v[46:49], v143 offset:51200
	ds_read_b128 v[50:53], v143 offset:51216
	ds_read_b128 v[54:57], v144
	ds_read_b128 v[58:61], v144 offset:16
	s_waitcnt lgkmcnt(0)
	v_add_u32_e32 v143, 32, v143
	v_add_u32_e32 v144, 32, v144
	ds_read_b128 v[62:65], v143 offset:2048
	ds_read_b128 v[66:69], v143 offset:2064
	ds_read_b128 v[70:73], v143 offset:18432
	ds_read_b128 v[74:77], v143 offset:18448
	ds_read_b128 v[78:81], v143 offset:34816
	ds_read_b128 v[82:85], v143 offset:34832
	ds_read_b128 v[86:89], v143 offset:51200
	ds_read_b128 v[90:93], v143 offset:51216
	ds_read_b128 v[94:97], v144
	ds_read_b128 v[98:101], v144 offset:16
	s_waitcnt vmcnt(24)
	v_pk_fma_f32 v[132:133], v[146:147], v[22:23], v[132:133]
	v_pk_fma_f32 v[134:135], v[146:147], v[30:31], v[134:135]
	v_pk_fma_f32 v[136:137], v[146:147], v[38:39], v[136:137]
	v_pk_fma_f32 v[138:139], v[146:147], v[46:47], v[138:139]
	v_pk_fma_f32 v[140:141], v[146:147], v[54:55], v[140:141]
	v_pk_fma_f32 v[132:133], v[148:149], v[24:25], v[132:133]
	v_pk_fma_f32 v[134:135], v[148:149], v[32:33], v[134:135]
	v_pk_fma_f32 v[136:137], v[148:149], v[40:41], v[136:137]
	v_pk_fma_f32 v[138:139], v[148:149], v[48:49], v[138:139]
	v_pk_fma_f32 v[140:141], v[148:149], v[56:57], v[140:141]
	v_pk_fma_f32 v[132:133], v[150:151], v[26:27], v[132:133]
	v_pk_fma_f32 v[134:135], v[150:151], v[34:35], v[134:135]
	v_pk_fma_f32 v[136:137], v[150:151], v[42:43], v[136:137]
	v_pk_fma_f32 v[138:139], v[150:151], v[50:51], v[138:139]
	v_pk_fma_f32 v[140:141], v[150:151], v[58:59], v[140:141]
	v_pk_fma_f32 v[132:133], v[152:153], v[28:29], v[132:133]
	v_pk_fma_f32 v[134:135], v[152:153], v[36:37], v[134:135]
	v_pk_fma_f32 v[136:137], v[152:153], v[44:45], v[136:137]
	v_pk_fma_f32 v[138:139], v[152:153], v[52:53], v[138:139]
	v_pk_fma_f32 v[140:141], v[152:153], v[60:61], v[140:141]
	s_waitcnt lgkmcnt(0)
	v_add_u32_e32 v143, 32, v143
	v_add_u32_e32 v144, 32, v144
	ds_read_b128 v[22:25], v143 offset:2048
	ds_read_b128 v[26:29], v143 offset:2064
	ds_read_b128 v[30:33], v143 offset:18432
	ds_read_b128 v[34:37], v143 offset:18448
	ds_read_b128 v[38:41], v143 offset:34816
	ds_read_b128 v[42:45], v143 offset:34832
	ds_read_b128 v[46:49], v143 offset:51200
	ds_read_b128 v[50:53], v143 offset:51216
	ds_read_b128 v[54:57], v144
	ds_read_b128 v[58:61], v144 offset:16
	s_waitcnt vmcnt(16)
	v_pk_fma_f32 v[132:133], v[154:155], v[62:63], v[132:133]
	v_pk_fma_f32 v[134:135], v[154:155], v[70:71], v[134:135]
	v_pk_fma_f32 v[136:137], v[154:155], v[78:79], v[136:137]
	v_pk_fma_f32 v[138:139], v[154:155], v[86:87], v[138:139]
	v_pk_fma_f32 v[140:141], v[154:155], v[94:95], v[140:141]
	v_pk_fma_f32 v[132:133], v[156:157], v[64:65], v[132:133]
	v_pk_fma_f32 v[134:135], v[156:157], v[72:73], v[134:135]
	v_pk_fma_f32 v[136:137], v[156:157], v[80:81], v[136:137]
	v_pk_fma_f32 v[138:139], v[156:157], v[88:89], v[138:139]
	v_pk_fma_f32 v[140:141], v[156:157], v[96:97], v[140:141]
	v_pk_fma_f32 v[132:133], v[158:159], v[66:67], v[132:133]
	v_pk_fma_f32 v[134:135], v[158:159], v[74:75], v[134:135]
	v_pk_fma_f32 v[136:137], v[158:159], v[82:83], v[136:137]
	v_pk_fma_f32 v[138:139], v[158:159], v[90:91], v[138:139]
	v_pk_fma_f32 v[140:141], v[158:159], v[98:99], v[140:141]
	v_pk_fma_f32 v[132:133], v[160:161], v[68:69], v[132:133]
	v_pk_fma_f32 v[134:135], v[160:161], v[76:77], v[134:135]
	v_pk_fma_f32 v[136:137], v[160:161], v[84:85], v[136:137]
	v_pk_fma_f32 v[138:139], v[160:161], v[92:93], v[138:139]
	v_pk_fma_f32 v[140:141], v[160:161], v[100:101], v[140:141]
	s_waitcnt lgkmcnt(0)
	v_add_u32_e32 v143, 32, v143
	v_add_u32_e32 v144, 32, v144
	ds_read_b128 v[62:65], v143 offset:2048
	ds_read_b128 v[66:69], v143 offset:2064
	ds_read_b128 v[70:73], v143 offset:18432
	ds_read_b128 v[74:77], v143 offset:18448
	ds_read_b128 v[78:81], v143 offset:34816
	ds_read_b128 v[82:85], v143 offset:34832
	ds_read_b128 v[86:89], v143 offset:51200
	ds_read_b128 v[90:93], v143 offset:51216
	ds_read_b128 v[94:97], v144
	ds_read_b128 v[98:101], v144 offset:16
	s_waitcnt vmcnt(8)
	v_pk_fma_f32 v[132:133], v[162:163], v[22:23], v[132:133]
	v_pk_fma_f32 v[134:135], v[162:163], v[30:31], v[134:135]
	v_pk_fma_f32 v[136:137], v[162:163], v[38:39], v[136:137]
	v_pk_fma_f32 v[138:139], v[162:163], v[46:47], v[138:139]
	v_pk_fma_f32 v[140:141], v[162:163], v[54:55], v[140:141]
	v_pk_fma_f32 v[132:133], v[164:165], v[24:25], v[132:133]
	v_pk_fma_f32 v[134:135], v[164:165], v[32:33], v[134:135]
	v_pk_fma_f32 v[136:137], v[164:165], v[40:41], v[136:137]
	v_pk_fma_f32 v[138:139], v[164:165], v[48:49], v[138:139]
	v_pk_fma_f32 v[140:141], v[164:165], v[56:57], v[140:141]
	v_pk_fma_f32 v[132:133], v[166:167], v[26:27], v[132:133]
	v_pk_fma_f32 v[134:135], v[166:167], v[34:35], v[134:135]
	v_pk_fma_f32 v[136:137], v[166:167], v[42:43], v[136:137]
	v_pk_fma_f32 v[138:139], v[166:167], v[50:51], v[138:139]
	v_pk_fma_f32 v[140:141], v[166:167], v[58:59], v[140:141]
	v_pk_fma_f32 v[132:133], v[168:169], v[28:29], v[132:133]
	v_pk_fma_f32 v[134:135], v[168:169], v[36:37], v[134:135]
	v_pk_fma_f32 v[136:137], v[168:169], v[44:45], v[136:137]
	v_pk_fma_f32 v[138:139], v[168:169], v[52:53], v[138:139]
	v_pk_fma_f32 v[140:141], v[168:169], v[60:61], v[140:141]
	s_waitcnt lgkmcnt(0)
	s_waitcnt vmcnt(0)
	v_pk_fma_f32 v[132:133], v[170:171], v[62:63], v[132:133]
	v_pk_fma_f32 v[134:135], v[170:171], v[70:71], v[134:135]
	v_pk_fma_f32 v[136:137], v[170:171], v[78:79], v[136:137]
	v_pk_fma_f32 v[138:139], v[170:171], v[86:87], v[138:139]
	v_pk_fma_f32 v[140:141], v[170:171], v[94:95], v[140:141]
	v_pk_fma_f32 v[132:133], v[172:173], v[64:65], v[132:133]
	v_pk_fma_f32 v[134:135], v[172:173], v[72:73], v[134:135]
	v_pk_fma_f32 v[136:137], v[172:173], v[80:81], v[136:137]
	v_pk_fma_f32 v[138:139], v[172:173], v[88:89], v[138:139]
	v_pk_fma_f32 v[140:141], v[172:173], v[96:97], v[140:141]
	v_pk_fma_f32 v[132:133], v[174:175], v[66:67], v[132:133]
	v_pk_fma_f32 v[134:135], v[174:175], v[74:75], v[134:135]
	v_pk_fma_f32 v[136:137], v[174:175], v[82:83], v[136:137]
	v_pk_fma_f32 v[138:139], v[174:175], v[90:91], v[138:139]
	v_pk_fma_f32 v[140:141], v[174:175], v[98:99], v[140:141]
	v_pk_fma_f32 v[132:133], v[176:177], v[68:69], v[132:133]
	v_pk_fma_f32 v[134:135], v[176:177], v[76:77], v[134:135]
	v_pk_fma_f32 v[136:137], v[176:177], v[84:85], v[136:137]
	v_pk_fma_f32 v[138:139], v[176:177], v[92:93], v[138:139]
	v_pk_fma_f32 v[140:141], v[176:177], v[100:101], v[140:141]
	s_addk_i32 s0, 0x80
	s_cmp_eq_u32 s0, 0
	s_cbranch_scc0 .LBB0_34
	v_add_f32_e32 v12, v132, v133
	v_add_f32_e32 v13, v134, v135
	v_add_f32_e32 v14, v136, v137
	v_add_f32_e32 v15, v138, v139
	v_add_f32_e32 v21, v140, v141
	ds_write2st64_b32 v17, v12, v13 offset1:1
	ds_write2st64_b32 v17, v14, v15 offset0:2 offset1:3
	ds_write_b32 v17, v21 offset:1024
	s_waitcnt lgkmcnt(0)
	s_barrier
	s_and_saveexec_b64 s[46:47], s[40:41]
	s_cbranch_execz .LBB0_16
	s_lshl_b32 s50, s56, 6
	v_add_u32_e32 v10, s50, v2
	v_ashrrev_i32_e32 v11, 31, v10
	v_lshl_add_u64 v[10:11], v[10:11], 2, s[12:13]
	global_load_dword v21, v[10:11], off nt
	ds_read2st64_b32 v[10:11], v20 offset1:5
	ds_read2st64_b32 v[12:13], v20 offset0:10 offset1:15
	ds_read2st64_b32 v[14:15], v20 offset0:20 offset1:25
	ds_read2st64_b32 v[22:23], v20 offset0:30 offset1:35
	s_ashr_i32 s51, s50, 31
	s_waitcnt lgkmcnt(3)
	v_add_f32_e32 v10, 0, v10
	v_add_f32_e32 v10, v10, v11
	s_waitcnt lgkmcnt(2)
	v_add_f32_e32 v10, v10, v12
	v_add_f32_e32 v10, v10, v13
	s_waitcnt lgkmcnt(1)
	v_add_f32_e32 v10, v10, v14
	v_add_f32_e32 v10, v10, v15
	s_waitcnt lgkmcnt(0)
	v_add_f32_e32 v10, v10, v22
	v_add_f32_e32 v10, v10, v23
	s_waitcnt vmcnt(0)
	v_add_f32_e32 v12, v10, v21
	v_lshl_add_u64 v[10:11], s[50:51], 2, v[4:5]
	global_store_dword v[10:11], v12, off
	s_branch .LBB0_16

.Lpb_next:
	s_add_i32 s65, s65, s3
	s_cmpk_lt_i32 s65, 0x440
	s_cbranch_scc1 .Lpb_loop
	s_branch .LBB0_178
	s_nop 0
	s_nop 0
	s_nop 0
	s_nop 0
	s_nop 0
	s_nop 0
	s_nop 0
	s_nop 0
	s_nop 0
	s_nop 0
	s_nop 0
	s_nop 0
	s_nop 0
	s_nop 0
	s_nop 0
	s_nop 0
	s_nop 0
	s_nop 0
	s_nop 0
	s_nop 0
	s_nop 0
	s_branch .LBB0_178
	s_nop 0
	s_nop 0
	s_nop 0
	s_nop 0
	s_nop 0
	s_nop 0
	s_nop 0
	s_nop 0
	s_nop 0
	s_nop 0
	s_nop 0
	s_nop 0
	s_nop 0
	s_nop 0
	s_nop 0
	s_nop 0
	s_nop 0
	s_nop 0
	s_nop 0
.LBB0_178:
	v_readlane_b32 s0, v255, 10
	v_readlane_b32 s60, v255, 0
	s_add_i32 s0, s0, 2
	v_readlane_b32 s63, v255, 3
	v_readlane_b32 s62, v255, 2
	s_cmp_ge_i32 s0, s63
	s_barrier
	v_readlane_b32 s61, v255, 1
	s_cbranch_scc1 .LBB0_190
	s_waitcnt vmcnt(0)
	s_barrier
	s_mov_b64 s[4:5], exec
	v_readlane_b32 s6, v254, 56
	v_readlane_b32 s7, v254, 57
	v_readlane_b32 s60, v255, 6
	s_and_b64 s[6:7], s[4:5], s[6:7]
	v_readlane_b32 s61, v255, 7
	s_mov_b64 exec, s[6:7]
	s_cbranch_execz .LBB0_228
	v_readlane_b32 s2, v253, 2
	s_waitcnt vmcnt(0) expcnt(0) lgkmcnt(0)
	s_nop 0
	v_mov_b32_e32 v2, s2
	ds_read_b32 v4, v2
	ds_read_b32 v2, v2 offset:4
	s_waitcnt lgkmcnt(1)
	v_cmp_ne_u32_e32 vcc, 0, v4
	s_cbranch_vccnz .LBB0_196
	v_readlane_b32 s8, v253, 0
	v_readlane_b32 s9, v253, 1
	s_load_dwordx2 s[6:7], s[8:9], 0x4
	s_mov_b32 s12, 1
	s_waitcnt lgkmcnt(0)
	s_mul_i32 s2, s6, s3
	s_mul_i32 s2, s2, s7
	s_branch .LBB0_183

.LBB0_265:
	v_readlane_b32 s6, v254, 4
	v_readlane_b32 s7, v254, 5
	v_cvt_f32_u32_e32 v3, v4
	v_sub_u32_e32 v6, 0, v4
	v_rcp_iflag_f32_e32 v3, v3
	s_nop 1
	global_atomic_add v5, v195, v197, s[6:7] sc0
	v_mul_f32_e32 v3, 0x4f7ffffe, v3
	v_cvt_u32_f32_e32 v3, v3
	v_mul_lo_u32 v6, v6, v3
	v_mul_hi_u32 v6, v3, v6
	v_add_u32_e32 v3, v3, v6
	s_waitcnt vmcnt(0)
	v_mul_hi_u32 v3, v5, v3
	v_mul_lo_u32 v6, v3, v4
	v_sub_u32_e32 v6, v5, v6
	v_add_u32_e32 v7, 1, v3
	v_cmp_ge_u32_e32 vcc, v6, v4
	v_add_u32_e32 v5, 1, v5
	s_nop 0
	v_cndmask_b32_e32 v3, v3, v7, vcc
	v_sub_u32_e32 v7, v6, v4
	v_cndmask_b32_e32 v6, v6, v7, vcc
	v_add_u32_e32 v7, 1, v3
	v_cmp_ge_u32_e32 vcc, v6, v4
	s_nop 1
	v_cndmask_b32_e32 v3, v3, v7, vcc
	v_mul_lo_u32 v6, v4, v3
	v_add_u32_e32 v4, v6, v4
	v_cmp_ne_u32_e32 vcc, v5, v4
	s_and_saveexec_b64 s[6:7], vcc
	s_xor_b64 s[6:7], exec, s[6:7]
	s_cbranch_execz .LBB0_279
	v_readlane_b32 s8, v254, 6
	v_readlane_b32 s9, v254, 7
	s_waitcnt lgkmcnt(0)
	s_nop 3
	global_load_dword v2, v195, s[8:9] sc1
	s_waitcnt vmcnt(0)
	v_cmp_eq_u32_e32 vcc, v2, v3
	s_and_saveexec_b64 s[8:9], vcc
	s_cbranch_execz .LBB0_278
	s_mov_b32 s2, 1
	s_mov_b64 s[10:11], 0
	s_branch .LBB0_269
.Lmy_tr_acall:
	s_branch .Lmy_a_entry
.Lmy_tr_dret:
	s_branch .Lmy_d_ret
.LBB0_268:
	s_and_b64 s[38:39], exec, s[38:39]
	s_or_b64 s[10:11], s[38:39], s[10:11]
	s_andn2_b64 s[12:13], s[12:13], exec
	s_and_b64 s[38:39], s[40:41], exec
	s_or_b64 s[12:13], s[12:13], s[38:39]
	s_andn2_b64 exec, exec, s[10:11]
	s_cbranch_execz .LBB0_275
